# m15 with the later code kept at m12's byte placement (48 bytes of unreachable padding after the gate/up tile loop)
# speedup vs baseline: 1.0115x; 1.0115x over previous
; __device__ __forceinline__ unsigned pk4_fp8(float a, float b, float c, float d) { int w = 0; w = __builtin_amdgcn_cvt_pk_fp8_f32(clamp8(a), clamp8(b), w, false); w = __builtin_amdgcn_cvt_pk_fp8_f32(clamp8(c), clamp8(d), w, true); return (unsigned)w; }
; __device__ __forceinline__ float silu_mul(float g, float u) { return g * __builtin_amdgcn_rcpf(1.0f + __builtin_amdgcn_exp2f(-g * LOG2E)) * u; }
;     __device__ __forceinline__ void operator()(const f32x4 (&acc)[2][2][4][2], const Unit& u, int wr, int wc, int fr, int fq, const unsigned long long (&pf)[8]) const {
;         const int row0 = u.pm * BM + wr * 64 + fr, col0 = u.pn * HALF + wc * 32 + 8 * fq;
; #pragma unroll
;         for (int ai = 0; ai < 2; ++ai)
; #pragma unroll
;             for (int m = 0; m < 4; ++m) { const int row = row0 + ai * HALF + m * 16; const float rs = rsqrtf((float)pf[ai * 4 + m] * (1.0f / (SSQ_SCALE * 1024.0f)) + EPS) * wsc;
;                 const f32x4 g0 = acc[ai][0][m][0] * rs, g1 = acc[ai][0][m][1] * rs, u0 = acc[ai][1][m][0] * rs, u1 = acc[ai][1][m][1] * rs;
;                 u32x2 w; w.x = pk4_fp8(silu_mul(g0[0], u0[0]) * HFF8_SCALE, silu_mul(g0[1], u0[1]) * HFF8_SCALE, silu_mul(g0[2], u0[2]) * HFF8_SCALE, silu_mul(g0[3], u0[3]) * HFF8_SCALE);
.LBB0_246:
	s_nop 15
	s_nop 7
	s_waitcnt vmcnt(0)
	v_lshl_or_b32 v0, s33, 7, v220
	v_mov_b32_e32 v4, 0x358637bd
	v_ashrrev_i32_e32 v1, 31, v0
	v_mov_b64_e32 v[2:3], s[48:49]
	v_and_b32_e32 v5, 8, v220
	v_mul_u32_u24_e32 v5, 0x15ff, v5
	v_add_u32_e32 v0, v0, v5
	v_mov_b32_e32 v6, 1.0
	v_mov_b32_e32 v7, 1.0
	v_ffbh_u32_e32 v8, v183
	v_ffbh_u32_e32 v12, v181
	v_min_u32_e32 v10, 32, v8
	v_min_u32_e32 v14, 32, v12
	v_lshlrev_b64 v[8:9], v10, v[182:183]
	v_lshlrev_b64 v[12:13], v14, v[180:181]
	v_min_u32_e32 v8, 1, v8
	v_min_u32_e32 v12, 1, v12
	v_or_b32_e32 v8, v9, v8
	v_or_b32_e32 v12, v13, v12
	v_cvt_f32_u32_e32 v8, v8
	v_cvt_f32_u32_e32 v12, v12
	v_sub_u32_e32 v9, 32, v10
	v_sub_u32_e32 v13, 32, v14
	v_ldexp_f32 v8, v8, v9
	v_ldexp_f32 v12, v12, v13
	v_fma_f32 v8, v8, s80, v4
	v_fma_f32 v12, v12, s80, v4
	v_mul_f32_e32 v9, 0x4b800000, v8
	v_mul_f32_e32 v13, 0x4b800000, v12
	v_cmp_gt_f32_e32 vcc, s92, v8
	v_cmp_gt_f32_e64 s[12:13], s92, v12
	s_nop 0
	v_cndmask_b32_e32 v8, v8, v9, vcc
	v_cndmask_b32_e64 v12, v12, v13, s[12:13]
	v_rsq_f32_e32 v8, v8
	v_rsq_f32_e32 v12, v12
	v_mul_f32_e32 v9, 0x45800000, v8
	v_mul_f32_e32 v13, 0x45800000, v12
	v_cndmask_b32_e32 v8, v8, v9, vcc
	v_cndmask_b32_e64 v12, v12, v13, s[12:13]
	v_mul_f32_e32 v8, 0x3c800000, v8
	v_mul_f32_e32 v12, 0x3c800000, v12
	v_mul_f32_e32 v194, 0xbfb8aa3b, v8
	v_mul_f32_e32 v196, 0xbfb8aa3b, v12
	v_mul_f32_e32 v9, v8, v8
	v_mul_f32_e32 v13, v12, v12
	v_mul_f32_e32 v195, 0x41000000, v9
	v_mul_f32_e32 v197, 0x41000000, v13
	v_ffbh_u32_e32 v8, v185
	v_ffbh_u32_e32 v12, v179
	v_min_u32_e32 v10, 32, v8
	v_min_u32_e32 v14, 32, v12
	v_lshlrev_b64 v[8:9], v10, v[184:185]
	v_lshlrev_b64 v[12:13], v14, v[178:179]
	v_min_u32_e32 v8, 1, v8
	v_min_u32_e32 v12, 1, v12
	v_or_b32_e32 v8, v9, v8
	v_or_b32_e32 v12, v13, v12
	v_cvt_f32_u32_e32 v8, v8
	v_cvt_f32_u32_e32 v12, v12
	v_sub_u32_e32 v9, 32, v10
	v_sub_u32_e32 v13, 32, v14
	v_ldexp_f32 v8, v8, v9
	v_ldexp_f32 v12, v12, v13
	v_fma_f32 v8, v8, s80, v4
	v_fma_f32 v12, v12, s80, v4
	v_mul_f32_e32 v9, 0x4b800000, v8
	v_mul_f32_e32 v13, 0x4b800000, v12
	v_cmp_gt_f32_e32 vcc, s92, v8
	v_cmp_gt_f32_e64 s[12:13], s92, v12
	s_nop 0
	v_cndmask_b32_e32 v8, v8, v9, vcc
	v_cndmask_b32_e64 v12, v12, v13, s[12:13]
	v_rsq_f32_e32 v8, v8
	v_rsq_f32_e32 v12, v12
	v_mul_f32_e32 v9, 0x45800000, v8
	v_mul_f32_e32 v13, 0x45800000, v12
	v_cndmask_b32_e32 v8, v8, v9, vcc
	v_cndmask_b32_e64 v12, v12, v13, s[12:13]
	v_mul_f32_e32 v8, 0x3c800000, v8
	v_mul_f32_e32 v12, 0x3c800000, v12
	v_mul_f32_e32 v198, 0xbfb8aa3b, v8
	v_mul_f32_e32 v200, 0xbfb8aa3b, v12
	v_mul_f32_e32 v9, v8, v8
	v_mul_f32_e32 v13, v12, v12
	v_mul_f32_e32 v199, 0x41000000, v9
	v_mul_f32_e32 v201, 0x41000000, v13
	v_ffbh_u32_e32 v8, v187
	v_ffbh_u32_e32 v12, v177
	v_min_u32_e32 v10, 32, v8
	v_min_u32_e32 v14, 32, v12
	v_lshlrev_b64 v[8:9], v10, v[186:187]
	v_lshlrev_b64 v[12:13], v14, v[176:177]
	v_min_u32_e32 v8, 1, v8
	v_min_u32_e32 v12, 1, v12
	v_or_b32_e32 v8, v9, v8
	v_or_b32_e32 v12, v13, v12
	v_cvt_f32_u32_e32 v8, v8
	v_cvt_f32_u32_e32 v12, v12
	v_sub_u32_e32 v9, 32, v10
	v_sub_u32_e32 v13, 32, v14
	v_ldexp_f32 v8, v8, v9
	v_ldexp_f32 v12, v12, v13
	v_fma_f32 v8, v8, s80, v4
	v_fma_f32 v12, v12, s80, v4
	v_mul_f32_e32 v9, 0x4b800000, v8
	v_mul_f32_e32 v13, 0x4b800000, v12
	v_cmp_gt_f32_e32 vcc, s92, v8
	v_cmp_gt_f32_e64 s[12:13], s92, v12
	s_nop 0
	v_cndmask_b32_e32 v8, v8, v9, vcc
	v_cndmask_b32_e64 v12, v12, v13, s[12:13]
	v_rsq_f32_e32 v8, v8
	v_rsq_f32_e32 v12, v12
	v_mul_f32_e32 v9, 0x45800000, v8
	v_mul_f32_e32 v13, 0x45800000, v12
	v_cndmask_b32_e32 v8, v8, v9, vcc
	v_cndmask_b32_e64 v12, v12, v13, s[12:13]
	v_mul_f32_e32 v8, 0x3c800000, v8
	v_mul_f32_e32 v12, 0x3c800000, v12
	v_mul_f32_e32 v246, 0xbfb8aa3b, v8
	v_mul_f32_e32 v248, 0xbfb8aa3b, v12
	v_mul_f32_e32 v9, v8, v8
	v_mul_f32_e32 v13, v12, v12
	v_mul_f32_e32 v247, 0x41000000, v9
	v_mul_f32_e32 v249, 0x41000000, v13
	v_ffbh_u32_e32 v8, v189
	v_ffbh_u32_e32 v12, v175
	v_min_u32_e32 v10, 32, v8
	v_min_u32_e32 v14, 32, v12
	v_lshlrev_b64 v[8:9], v10, v[188:189]
	v_lshlrev_b64 v[12:13], v14, v[174:175]
	v_min_u32_e32 v8, 1, v8
	v_min_u32_e32 v12, 1, v12
	v_or_b32_e32 v8, v9, v8
	v_or_b32_e32 v12, v13, v12
	v_cvt_f32_u32_e32 v8, v8
	v_cvt_f32_u32_e32 v12, v12
	v_sub_u32_e32 v9, 32, v10
	v_sub_u32_e32 v13, 32, v14
	v_ldexp_f32 v8, v8, v9
	v_ldexp_f32 v12, v12, v13
	v_fma_f32 v8, v8, s80, v4
	v_fma_f32 v12, v12, s80, v4
	v_mul_f32_e32 v9, 0x4b800000, v8
	v_mul_f32_e32 v13, 0x4b800000, v12
	v_cmp_gt_f32_e32 vcc, s92, v8
	v_cmp_gt_f32_e64 s[12:13], s92, v12
	s_nop 0
	v_cndmask_b32_e32 v8, v8, v9, vcc
	v_cndmask_b32_e64 v12, v12, v13, s[12:13]
	v_rsq_f32_e32 v8, v8
	v_rsq_f32_e32 v12, v12
	v_mul_f32_e32 v9, 0x45800000, v8
	v_mul_f32_e32 v13, 0x45800000, v12
	v_cndmask_b32_e32 v8, v8, v9, vcc
	v_cndmask_b32_e64 v12, v12, v13, s[12:13]
	v_mul_f32_e32 v8, 0x3c800000, v8
	v_mul_f32_e32 v12, 0x3c800000, v12
	v_mul_f32_e32 v250, 0xbfb8aa3b, v8
	v_mul_f32_e32 v252, 0xbfb8aa3b, v12
	v_mul_f32_e32 v9, v8, v8
	v_mul_f32_e32 v13, v12, v12
	v_mul_f32_e32 v251, 0x41000000, v9
	v_mul_f32_e32 v253, 0x41000000, v13
	v_pk_mul_f32 v[222:223], v[156:157], v[194:195] op_sel_hi:[1,0]
	v_pk_mul_f32 v[224:225], v[158:159], v[194:195] op_sel_hi:[1,0]
	v_pk_mul_f32 v[226:227], v[152:153], v[194:195] op_sel_hi:[1,0]
	v_pk_mul_f32 v[228:229], v[154:155], v[194:195] op_sel_hi:[1,0]
	v_mad_i64_i32 v[16:17], vcc, v190, s93, v[2:3]
	v_exp_f32_e32 v222, v222
	v_exp_f32_e32 v223, v223
	v_exp_f32_e32 v224, v224
	v_exp_f32_e32 v225, v225
	v_exp_f32_e32 v226, v226
	v_exp_f32_e32 v227, v227
	v_exp_f32_e32 v228, v228
	v_exp_f32_e32 v229, v229
	v_pk_mul_f32 v[238:239], v[156:157], v[148:149]
; __device__ __forceinline__ unsigned pk4_fp8(float a, float b, float c, float d) { int w = 0; w = __builtin_amdgcn_cvt_pk_fp8_f32(clamp8(a), clamp8(b), w, false); w = __builtin_amdgcn_cvt_pk_fp8_f32(clamp8(c), clamp8(d), w, true); return (unsigned)w; }
; __device__ __forceinline__ float silu_mul(float g, float u) { return g * __builtin_amdgcn_rcpf(1.0f + __builtin_amdgcn_exp2f(-g * LOG2E)) * u; }
;     __device__ __forceinline__ void operator()(const f32x4 (&acc)[2][2][4][2], const Unit& u, int wr, int wc, int fr, int fq, const unsigned long long (&pf)[8]) const {
;     ...
;             for (int m = 0; m < 4; ++m) { const int row = row0 + ai * HALF + m * 16; const float rs = rsqrtf((float)pf[ai * 4 + m] * (1.0f / (SSQ_SCALE * 1024.0f)) + EPS) * wsc;
;                 const f32x4 g0 = acc[ai][0][m][0] * rs, g1 = acc[ai][0][m][1] * rs, u0 = acc[ai][1][m][0] * rs, u1 = acc[ai][1][m][1] * rs;
;                 u32x2 w; w.x = pk4_fp8(silu_mul(g0[0], u0[0]) * HFF8_SCALE, silu_mul(g0[1], u0[1]) * HFF8_SCALE, silu_mul(g0[2], u0[2]) * HFF8_SCALE, silu_mul(g0[3], u0[3]) * HFF8_SCALE);
;                 w.y = pk4_fp8(silu_mul(g1[0], u1[0]) * HFF8_SCALE, silu_mul(g1[1], u1[1]) * HFF8_SCALE, silu_mul(g1[2], u1[2]) * HFF8_SCALE, silu_mul(g1[3], u1[3]) * HFF8_SCALE);
;                 *(u32x2*)(O + (size_t)row * FF + col0) = w; }
	v_pk_mul_f32 v[240:241], v[158:159], v[150:151]
	v_pk_mul_f32 v[242:243], v[152:153], v[144:145]
	v_pk_mul_f32 v[244:245], v[154:155], v[146:147]
	v_pk_add_f32 v[230:231], v[222:223], v[6:7]
	v_pk_add_f32 v[232:233], v[224:225], v[6:7]
	v_pk_add_f32 v[234:235], v[226:227], v[6:7]
	v_pk_add_f32 v[236:237], v[228:229], v[6:7]
	v_lshl_add_u64 v[16:17], v[16:17], 0, v[0:1]
	v_rcp_f32_e32 v230, v230
	v_rcp_f32_e32 v231, v231
	v_rcp_f32_e32 v232, v232
	v_rcp_f32_e32 v233, v233
	v_rcp_f32_e32 v234, v234
	v_rcp_f32_e32 v235, v235
	v_rcp_f32_e32 v236, v236
	v_rcp_f32_e32 v237, v237
	v_pk_mul_f32 v[238:239], v[238:239], v[194:195] op_sel:[0,1] op_sel_hi:[1,1]
	v_pk_mul_f32 v[240:241], v[240:241], v[194:195] op_sel:[0,1] op_sel_hi:[1,1]
	v_pk_mul_f32 v[242:243], v[242:243], v[194:195] op_sel:[0,1] op_sel_hi:[1,1]
	v_pk_mul_f32 v[244:245], v[244:245], v[194:195] op_sel:[0,1] op_sel_hi:[1,1]
	v_pk_mul_f32 v[238:239], v[238:239], v[230:231]
	v_pk_mul_f32 v[240:241], v[240:241], v[232:233]
	v_pk_mul_f32 v[242:243], v[242:243], v[234:235]
	v_pk_mul_f32 v[244:245], v[244:245], v[236:237]
	v_med3_f32 v238, v238, s38, v210
	v_med3_f32 v239, v239, s38, v210
	v_med3_f32 v240, v240, s38, v210
	v_med3_f32 v241, v241, s38, v210
	v_med3_f32 v242, v242, s38, v210
	v_med3_f32 v243, v243, s38, v210
	v_med3_f32 v244, v244, s38, v210
	v_med3_f32 v245, v245, s38, v210
	v_cvt_pk_fp8_f32 v20, v238, v239
	v_cvt_pk_fp8_f32 v21, v242, v243
	v_cvt_pk_fp8_f32 v20, v240, v241 op_sel:[0,0,1]
	v_cvt_pk_fp8_f32 v21, v244, v245 op_sel:[0,0,1]
	v_add_u32_e32 v24, 0x10, v190
	v_pk_mul_f32 v[222:223], v[140:141], v[196:197] op_sel_hi:[1,0]
	v_pk_mul_f32 v[224:225], v[142:143], v[196:197] op_sel_hi:[1,0]
	v_pk_mul_f32 v[226:227], v[136:137], v[196:197] op_sel_hi:[1,0]
	v_pk_mul_f32 v[228:229], v[138:139], v[196:197] op_sel_hi:[1,0]
	v_exp_f32_e32 v222, v222
	v_exp_f32_e32 v223, v223
	v_exp_f32_e32 v224, v224
	v_exp_f32_e32 v225, v225
	v_exp_f32_e32 v226, v226
	v_exp_f32_e32 v227, v227
	v_exp_f32_e32 v228, v228
	v_exp_f32_e32 v229, v229
	v_pk_mul_f32 v[238:239], v[140:141], v[132:133]
	v_pk_mul_f32 v[240:241], v[142:143], v[134:135]
	v_pk_mul_f32 v[242:243], v[136:137], v[128:129]
	v_pk_mul_f32 v[244:245], v[138:139], v[130:131]
	v_pk_add_f32 v[230:231], v[222:223], v[6:7]
	v_pk_add_f32 v[232:233], v[224:225], v[6:7]
	v_pk_add_f32 v[234:235], v[226:227], v[6:7]
	v_pk_add_f32 v[236:237], v[228:229], v[6:7]
	v_rcp_f32_e32 v230, v230
	v_rcp_f32_e32 v231, v231
	v_rcp_f32_e32 v232, v232
	v_rcp_f32_e32 v233, v233
	v_rcp_f32_e32 v234, v234
	v_rcp_f32_e32 v235, v235
	v_rcp_f32_e32 v236, v236
	v_rcp_f32_e32 v237, v237
	v_pk_mul_f32 v[238:239], v[238:239], v[196:197] op_sel:[0,1] op_sel_hi:[1,1]
	v_pk_mul_f32 v[240:241], v[240:241], v[196:197] op_sel:[0,1] op_sel_hi:[1,1]
	v_pk_mul_f32 v[242:243], v[242:243], v[196:197] op_sel:[0,1] op_sel_hi:[1,1]
	v_pk_mul_f32 v[244:245], v[244:245], v[196:197] op_sel:[0,1] op_sel_hi:[1,1]
	v_pk_mul_f32 v[238:239], v[238:239], v[230:231]
	v_pk_mul_f32 v[240:241], v[240:241], v[232:233]
	v_pk_mul_f32 v[242:243], v[242:243], v[234:235]
	v_pk_mul_f32 v[244:245], v[244:245], v[236:237]
	v_med3_f32 v238, v238, s38, v210
	v_med3_f32 v239, v239, s38, v210
	v_med3_f32 v240, v240, s38, v210
	v_med3_f32 v241, v241, s38, v210
	v_med3_f32 v242, v242, s38, v210
	v_med3_f32 v243, v243, s38, v210
	v_med3_f32 v244, v244, s38, v210
	v_med3_f32 v245, v245, s38, v210
	v_cvt_pk_fp8_f32 v22, v238, v239
	v_cvt_pk_fp8_f32 v23, v242, v243
	v_cvt_pk_fp8_f32 v22, v240, v241 op_sel:[0,0,1]
	v_cvt_pk_fp8_f32 v23, v244, v245 op_sel:[0,0,1]
	s_nop 1
	v_permlane16_swap_b32_e32 v20, v22
	v_permlane16_swap_b32_e32 v21, v23
	s_nop 0
	global_store_dwordx4 v[16:17], v[20:23], off
	v_add_u32_e32 v24, 0x20, v190
	v_pk_mul_f32 v[222:223], v[124:125], v[198:199] op_sel_hi:[1,0]
	v_pk_mul_f32 v[224:225], v[126:127], v[198:199] op_sel_hi:[1,0]
	v_pk_mul_f32 v[226:227], v[120:121], v[198:199] op_sel_hi:[1,0]
	v_pk_mul_f32 v[228:229], v[122:123], v[198:199] op_sel_hi:[1,0]
	v_mad_i64_i32 v[16:17], vcc, v24, s93, v[2:3]
	v_exp_f32_e32 v222, v222
	v_exp_f32_e32 v223, v223
	v_exp_f32_e32 v224, v224
	v_exp_f32_e32 v225, v225
	v_exp_f32_e32 v226, v226
	v_exp_f32_e32 v227, v227
	v_exp_f32_e32 v228, v228
	v_exp_f32_e32 v229, v229
	v_pk_mul_f32 v[238:239], v[124:125], v[116:117]
	v_pk_mul_f32 v[240:241], v[126:127], v[118:119]
	v_pk_mul_f32 v[242:243], v[120:121], v[112:113]
	v_pk_mul_f32 v[244:245], v[122:123], v[114:115]
	v_pk_add_f32 v[230:231], v[222:223], v[6:7]
	v_pk_add_f32 v[232:233], v[224:225], v[6:7]
	v_pk_add_f32 v[234:235], v[226:227], v[6:7]
	v_pk_add_f32 v[236:237], v[228:229], v[6:7]
	v_lshl_add_u64 v[16:17], v[16:17], 0, v[0:1]
	v_rcp_f32_e32 v230, v230
	v_rcp_f32_e32 v231, v231
	v_rcp_f32_e32 v232, v232
	v_rcp_f32_e32 v233, v233
	v_rcp_f32_e32 v234, v234
	v_rcp_f32_e32 v235, v235
	v_rcp_f32_e32 v236, v236
	v_rcp_f32_e32 v237, v237
	v_pk_mul_f32 v[238:239], v[238:239], v[198:199] op_sel:[0,1] op_sel_hi:[1,1]
	v_pk_mul_f32 v[240:241], v[240:241], v[198:199] op_sel:[0,1] op_sel_hi:[1,1]
	v_pk_mul_f32 v[242:243], v[242:243], v[198:199] op_sel:[0,1] op_sel_hi:[1,1]
	v_pk_mul_f32 v[244:245], v[244:245], v[198:199] op_sel:[0,1] op_sel_hi:[1,1]
	v_pk_mul_f32 v[238:239], v[238:239], v[230:231]
	v_pk_mul_f32 v[240:241], v[240:241], v[232:233]
	v_pk_mul_f32 v[242:243], v[242:243], v[234:235]
	v_pk_mul_f32 v[244:245], v[244:245], v[236:237]
	v_med3_f32 v238, v238, s38, v210
	v_med3_f32 v239, v239, s38, v210
	v_med3_f32 v240, v240, s38, v210
	v_med3_f32 v241, v241, s38, v210
	v_med3_f32 v242, v242, s38, v210
	v_med3_f32 v243, v243, s38, v210
	v_med3_f32 v244, v244, s38, v210
	v_med3_f32 v245, v245, s38, v210
; __device__ __forceinline__ unsigned pk4_fp8(float a, float b, float c, float d) { int w = 0; w = __builtin_amdgcn_cvt_pk_fp8_f32(clamp8(a), clamp8(b), w, false); w = __builtin_amdgcn_cvt_pk_fp8_f32(clamp8(c), clamp8(d), w, true); return (unsigned)w; }
; __device__ __forceinline__ float silu_mul(float g, float u) { return g * __builtin_amdgcn_rcpf(1.0f + __builtin_amdgcn_exp2f(-g * LOG2E)) * u; }
;     __device__ __forceinline__ void operator()(const f32x4 (&acc)[2][2][4][2], const Unit& u, int wr, int wc, int fr, int fq, const unsigned long long (&pf)[8]) const {
;     ...
;             for (int m = 0; m < 4; ++m) { const int row = row0 + ai * HALF + m * 16; const float rs = rsqrtf((float)pf[ai * 4 + m] * (1.0f / (SSQ_SCALE * 1024.0f)) + EPS) * wsc;
;                 const f32x4 g0 = acc[ai][0][m][0] * rs, g1 = acc[ai][0][m][1] * rs, u0 = acc[ai][1][m][0] * rs, u1 = acc[ai][1][m][1] * rs;
;                 u32x2 w; w.x = pk4_fp8(silu_mul(g0[0], u0[0]) * HFF8_SCALE, silu_mul(g0[1], u0[1]) * HFF8_SCALE, silu_mul(g0[2], u0[2]) * HFF8_SCALE, silu_mul(g0[3], u0[3]) * HFF8_SCALE);
;                 w.y = pk4_fp8(silu_mul(g1[0], u1[0]) * HFF8_SCALE, silu_mul(g1[1], u1[1]) * HFF8_SCALE, silu_mul(g1[2], u1[2]) * HFF8_SCALE, silu_mul(g1[3], u1[3]) * HFF8_SCALE);
;                 *(u32x2*)(O + (size_t)row * FF + col0) = w; }
	v_cvt_pk_fp8_f32 v20, v238, v239
	v_cvt_pk_fp8_f32 v21, v242, v243
	v_cvt_pk_fp8_f32 v20, v240, v241 op_sel:[0,0,1]
	v_cvt_pk_fp8_f32 v21, v244, v245 op_sel:[0,0,1]
	v_add_u32_e32 v24, 0x30, v190
	v_pk_mul_f32 v[222:223], v[108:109], v[200:201] op_sel_hi:[1,0]
	v_pk_mul_f32 v[224:225], v[110:111], v[200:201] op_sel_hi:[1,0]
	v_pk_mul_f32 v[226:227], v[104:105], v[200:201] op_sel_hi:[1,0]
	v_pk_mul_f32 v[228:229], v[106:107], v[200:201] op_sel_hi:[1,0]
	v_exp_f32_e32 v222, v222
	v_exp_f32_e32 v223, v223
	v_exp_f32_e32 v224, v224
	v_exp_f32_e32 v225, v225
	v_exp_f32_e32 v226, v226
	v_exp_f32_e32 v227, v227
	v_exp_f32_e32 v228, v228
	v_exp_f32_e32 v229, v229
	v_pk_mul_f32 v[238:239], v[108:109], v[100:101]
	v_pk_mul_f32 v[240:241], v[110:111], v[102:103]
	v_pk_mul_f32 v[242:243], v[104:105], v[96:97]
	v_pk_mul_f32 v[244:245], v[106:107], v[98:99]
	v_pk_add_f32 v[230:231], v[222:223], v[6:7]
	v_pk_add_f32 v[232:233], v[224:225], v[6:7]
	v_pk_add_f32 v[234:235], v[226:227], v[6:7]
	v_pk_add_f32 v[236:237], v[228:229], v[6:7]
	v_rcp_f32_e32 v230, v230
	v_rcp_f32_e32 v231, v231
	v_rcp_f32_e32 v232, v232
	v_rcp_f32_e32 v233, v233
	v_rcp_f32_e32 v234, v234
	v_rcp_f32_e32 v235, v235
	v_rcp_f32_e32 v236, v236
	v_rcp_f32_e32 v237, v237
	v_pk_mul_f32 v[238:239], v[238:239], v[200:201] op_sel:[0,1] op_sel_hi:[1,1]
	v_pk_mul_f32 v[240:241], v[240:241], v[200:201] op_sel:[0,1] op_sel_hi:[1,1]
	v_pk_mul_f32 v[242:243], v[242:243], v[200:201] op_sel:[0,1] op_sel_hi:[1,1]
	v_pk_mul_f32 v[244:245], v[244:245], v[200:201] op_sel:[0,1] op_sel_hi:[1,1]
	v_pk_mul_f32 v[238:239], v[238:239], v[230:231]
	v_pk_mul_f32 v[240:241], v[240:241], v[232:233]
	v_pk_mul_f32 v[242:243], v[242:243], v[234:235]
	v_pk_mul_f32 v[244:245], v[244:245], v[236:237]
	v_med3_f32 v238, v238, s38, v210
	v_med3_f32 v239, v239, s38, v210
	v_med3_f32 v240, v240, s38, v210
	v_med3_f32 v241, v241, s38, v210
	v_med3_f32 v242, v242, s38, v210
	v_med3_f32 v243, v243, s38, v210
	v_med3_f32 v244, v244, s38, v210
	v_med3_f32 v245, v245, s38, v210
	v_cvt_pk_fp8_f32 v22, v238, v239
	v_cvt_pk_fp8_f32 v23, v242, v243
	v_cvt_pk_fp8_f32 v22, v240, v241 op_sel:[0,0,1]
	v_cvt_pk_fp8_f32 v23, v244, v245 op_sel:[0,0,1]
	s_nop 1
	v_permlane16_swap_b32_e32 v20, v22
	v_permlane16_swap_b32_e32 v21, v23
	s_nop 0
	global_store_dwordx4 v[16:17], v[20:23], off
	v_add_u32_e32 v24, 0x80, v190
	v_pk_mul_f32 v[222:223], v[92:93], v[246:247] op_sel_hi:[1,0]
	v_pk_mul_f32 v[224:225], v[94:95], v[246:247] op_sel_hi:[1,0]
	v_pk_mul_f32 v[226:227], v[88:89], v[246:247] op_sel_hi:[1,0]
	v_pk_mul_f32 v[228:229], v[90:91], v[246:247] op_sel_hi:[1,0]
	v_mad_i64_i32 v[16:17], vcc, v24, s93, v[2:3]
	v_exp_f32_e32 v222, v222
	v_exp_f32_e32 v223, v223
	v_exp_f32_e32 v224, v224
	v_exp_f32_e32 v225, v225
	v_exp_f32_e32 v226, v226
	v_exp_f32_e32 v227, v227
	v_exp_f32_e32 v228, v228
	v_exp_f32_e32 v229, v229
	v_pk_mul_f32 v[238:239], v[92:93], v[84:85]
	v_pk_mul_f32 v[240:241], v[94:95], v[86:87]
	v_pk_mul_f32 v[242:243], v[88:89], v[80:81]
	v_pk_mul_f32 v[244:245], v[90:91], v[82:83]
	v_pk_add_f32 v[230:231], v[222:223], v[6:7]
	v_pk_add_f32 v[232:233], v[224:225], v[6:7]
	v_pk_add_f32 v[234:235], v[226:227], v[6:7]
	v_pk_add_f32 v[236:237], v[228:229], v[6:7]
	v_lshl_add_u64 v[16:17], v[16:17], 0, v[0:1]
	v_rcp_f32_e32 v230, v230
	v_rcp_f32_e32 v231, v231
	v_rcp_f32_e32 v232, v232
	v_rcp_f32_e32 v233, v233
	v_rcp_f32_e32 v234, v234
	v_rcp_f32_e32 v235, v235
	v_rcp_f32_e32 v236, v236
	v_rcp_f32_e32 v237, v237
	v_pk_mul_f32 v[238:239], v[238:239], v[246:247] op_sel:[0,1] op_sel_hi:[1,1]
	v_pk_mul_f32 v[240:241], v[240:241], v[246:247] op_sel:[0,1] op_sel_hi:[1,1]
	v_pk_mul_f32 v[242:243], v[242:243], v[246:247] op_sel:[0,1] op_sel_hi:[1,1]
	v_pk_mul_f32 v[244:245], v[244:245], v[246:247] op_sel:[0,1] op_sel_hi:[1,1]
	v_pk_mul_f32 v[238:239], v[238:239], v[230:231]
	v_pk_mul_f32 v[240:241], v[240:241], v[232:233]
	v_pk_mul_f32 v[242:243], v[242:243], v[234:235]
	v_pk_mul_f32 v[244:245], v[244:245], v[236:237]
	v_med3_f32 v238, v238, s38, v210
	v_med3_f32 v239, v239, s38, v210
	v_med3_f32 v240, v240, s38, v210
	v_med3_f32 v241, v241, s38, v210
	v_med3_f32 v242, v242, s38, v210
	v_med3_f32 v243, v243, s38, v210
	v_med3_f32 v244, v244, s38, v210
	v_med3_f32 v245, v245, s38, v210
	v_cvt_pk_fp8_f32 v20, v238, v239
	v_cvt_pk_fp8_f32 v21, v242, v243
	v_cvt_pk_fp8_f32 v20, v240, v241 op_sel:[0,0,1]
	v_cvt_pk_fp8_f32 v21, v244, v245 op_sel:[0,0,1]
	v_add_u32_e32 v24, 0x90, v190
	v_pk_mul_f32 v[222:223], v[76:77], v[248:249] op_sel_hi:[1,0]
	v_pk_mul_f32 v[224:225], v[78:79], v[248:249] op_sel_hi:[1,0]
	v_pk_mul_f32 v[226:227], v[72:73], v[248:249] op_sel_hi:[1,0]
	v_pk_mul_f32 v[228:229], v[74:75], v[248:249] op_sel_hi:[1,0]
	v_exp_f32_e32 v222, v222
	v_exp_f32_e32 v223, v223
	v_exp_f32_e32 v224, v224
	v_exp_f32_e32 v225, v225
	v_exp_f32_e32 v226, v226
	v_exp_f32_e32 v227, v227
	v_exp_f32_e32 v228, v228
	v_exp_f32_e32 v229, v229
	v_pk_mul_f32 v[238:239], v[76:77], v[68:69]
	v_pk_mul_f32 v[240:241], v[78:79], v[70:71]
	v_pk_mul_f32 v[242:243], v[72:73], v[64:65]
	v_pk_mul_f32 v[244:245], v[74:75], v[66:67]
	v_pk_add_f32 v[230:231], v[222:223], v[6:7]
	v_pk_add_f32 v[232:233], v[224:225], v[6:7]
	v_pk_add_f32 v[234:235], v[226:227], v[6:7]
	v_pk_add_f32 v[236:237], v[228:229], v[6:7]
	v_rcp_f32_e32 v230, v230
	v_rcp_f32_e32 v231, v231
	v_rcp_f32_e32 v232, v232
	v_rcp_f32_e32 v233, v233
	v_rcp_f32_e32 v234, v234
	v_rcp_f32_e32 v235, v235
	v_rcp_f32_e32 v236, v236
	v_rcp_f32_e32 v237, v237
	v_pk_mul_f32 v[238:239], v[238:239], v[248:249] op_sel:[0,1] op_sel_hi:[1,1]
; __device__ __forceinline__ unsigned pk4_fp8(float a, float b, float c, float d) { int w = 0; w = __builtin_amdgcn_cvt_pk_fp8_f32(clamp8(a), clamp8(b), w, false); w = __builtin_amdgcn_cvt_pk_fp8_f32(clamp8(c), clamp8(d), w, true); return (unsigned)w; }
; __device__ __forceinline__ float silu_mul(float g, float u) { return g * __builtin_amdgcn_rcpf(1.0f + __builtin_amdgcn_exp2f(-g * LOG2E)) * u; }
;     __device__ __forceinline__ void operator()(const f32x4 (&acc)[2][2][4][2], const Unit& u, int wr, int wc, int fr, int fq, const unsigned long long (&pf)[8]) const {
;     ...
;             for (int m = 0; m < 4; ++m) { const int row = row0 + ai * HALF + m * 16; const float rs = rsqrtf((float)pf[ai * 4 + m] * (1.0f / (SSQ_SCALE * 1024.0f)) + EPS) * wsc;
;                 const f32x4 g0 = acc[ai][0][m][0] * rs, g1 = acc[ai][0][m][1] * rs, u0 = acc[ai][1][m][0] * rs, u1 = acc[ai][1][m][1] * rs;
;                 u32x2 w; w.x = pk4_fp8(silu_mul(g0[0], u0[0]) * HFF8_SCALE, silu_mul(g0[1], u0[1]) * HFF8_SCALE, silu_mul(g0[2], u0[2]) * HFF8_SCALE, silu_mul(g0[3], u0[3]) * HFF8_SCALE);
;                 w.y = pk4_fp8(silu_mul(g1[0], u1[0]) * HFF8_SCALE, silu_mul(g1[1], u1[1]) * HFF8_SCALE, silu_mul(g1[2], u1[2]) * HFF8_SCALE, silu_mul(g1[3], u1[3]) * HFF8_SCALE);
;                 *(u32x2*)(O + (size_t)row * FF + col0) = w; }
	v_pk_mul_f32 v[240:241], v[240:241], v[248:249] op_sel:[0,1] op_sel_hi:[1,1]
	v_pk_mul_f32 v[242:243], v[242:243], v[248:249] op_sel:[0,1] op_sel_hi:[1,1]
	v_pk_mul_f32 v[244:245], v[244:245], v[248:249] op_sel:[0,1] op_sel_hi:[1,1]
	v_pk_mul_f32 v[238:239], v[238:239], v[230:231]
	v_pk_mul_f32 v[240:241], v[240:241], v[232:233]
	v_pk_mul_f32 v[242:243], v[242:243], v[234:235]
	v_pk_mul_f32 v[244:245], v[244:245], v[236:237]
	v_med3_f32 v238, v238, s38, v210
	v_med3_f32 v239, v239, s38, v210
	v_med3_f32 v240, v240, s38, v210
	v_med3_f32 v241, v241, s38, v210
	v_med3_f32 v242, v242, s38, v210
	v_med3_f32 v243, v243, s38, v210
	v_med3_f32 v244, v244, s38, v210
	v_med3_f32 v245, v245, s38, v210
	v_cvt_pk_fp8_f32 v22, v238, v239
	v_cvt_pk_fp8_f32 v23, v242, v243
	v_cvt_pk_fp8_f32 v22, v240, v241 op_sel:[0,0,1]
	v_cvt_pk_fp8_f32 v23, v244, v245 op_sel:[0,0,1]
	s_nop 1
	v_permlane16_swap_b32_e32 v20, v22
	v_permlane16_swap_b32_e32 v21, v23
	s_nop 0
	global_store_dwordx4 v[16:17], v[20:23], off
	v_add_u32_e32 v24, 0xa0, v190
	v_pk_mul_f32 v[222:223], v[60:61], v[250:251] op_sel_hi:[1,0]
	v_pk_mul_f32 v[224:225], v[62:63], v[250:251] op_sel_hi:[1,0]
	v_pk_mul_f32 v[226:227], v[56:57], v[250:251] op_sel_hi:[1,0]
	v_pk_mul_f32 v[228:229], v[58:59], v[250:251] op_sel_hi:[1,0]
	v_mad_i64_i32 v[16:17], vcc, v24, s93, v[2:3]
	v_exp_f32_e32 v222, v222
	v_exp_f32_e32 v223, v223
	v_exp_f32_e32 v224, v224
	v_exp_f32_e32 v225, v225
	v_exp_f32_e32 v226, v226
	v_exp_f32_e32 v227, v227
	v_exp_f32_e32 v228, v228
	v_exp_f32_e32 v229, v229
	v_pk_mul_f32 v[238:239], v[60:61], v[52:53]
	v_pk_mul_f32 v[240:241], v[62:63], v[54:55]
	v_pk_mul_f32 v[242:243], v[56:57], v[48:49]
	v_pk_mul_f32 v[244:245], v[58:59], v[50:51]
	v_pk_add_f32 v[230:231], v[222:223], v[6:7]
	v_pk_add_f32 v[232:233], v[224:225], v[6:7]
	v_pk_add_f32 v[234:235], v[226:227], v[6:7]
	v_pk_add_f32 v[236:237], v[228:229], v[6:7]
	v_lshl_add_u64 v[16:17], v[16:17], 0, v[0:1]
	v_rcp_f32_e32 v230, v230
	v_rcp_f32_e32 v231, v231
	v_rcp_f32_e32 v232, v232
	v_rcp_f32_e32 v233, v233
	v_rcp_f32_e32 v234, v234
	v_rcp_f32_e32 v235, v235
	v_rcp_f32_e32 v236, v236
	v_rcp_f32_e32 v237, v237
	v_pk_mul_f32 v[238:239], v[238:239], v[250:251] op_sel:[0,1] op_sel_hi:[1,1]
	v_pk_mul_f32 v[240:241], v[240:241], v[250:251] op_sel:[0,1] op_sel_hi:[1,1]
	v_pk_mul_f32 v[242:243], v[242:243], v[250:251] op_sel:[0,1] op_sel_hi:[1,1]
	v_pk_mul_f32 v[244:245], v[244:245], v[250:251] op_sel:[0,1] op_sel_hi:[1,1]
	v_pk_mul_f32 v[238:239], v[238:239], v[230:231]
	v_pk_mul_f32 v[240:241], v[240:241], v[232:233]
	v_pk_mul_f32 v[242:243], v[242:243], v[234:235]
	v_pk_mul_f32 v[244:245], v[244:245], v[236:237]
	v_med3_f32 v238, v238, s38, v210
	v_med3_f32 v239, v239, s38, v210
	v_med3_f32 v240, v240, s38, v210
	v_med3_f32 v241, v241, s38, v210
	v_med3_f32 v242, v242, s38, v210
	v_med3_f32 v243, v243, s38, v210
	v_med3_f32 v244, v244, s38, v210
	v_med3_f32 v245, v245, s38, v210
	v_cvt_pk_fp8_f32 v20, v238, v239
	v_cvt_pk_fp8_f32 v21, v242, v243
	v_cvt_pk_fp8_f32 v20, v240, v241 op_sel:[0,0,1]
	v_cvt_pk_fp8_f32 v21, v244, v245 op_sel:[0,0,1]
	v_add_u32_e32 v24, 0xb0, v190
	v_pk_mul_f32 v[222:223], v[44:45], v[252:253] op_sel_hi:[1,0]
	v_pk_mul_f32 v[224:225], v[46:47], v[252:253] op_sel_hi:[1,0]
	v_pk_mul_f32 v[226:227], v[40:41], v[252:253] op_sel_hi:[1,0]
	v_pk_mul_f32 v[228:229], v[42:43], v[252:253] op_sel_hi:[1,0]
	v_exp_f32_e32 v222, v222
	v_exp_f32_e32 v223, v223
	v_exp_f32_e32 v224, v224
	v_exp_f32_e32 v225, v225
	v_exp_f32_e32 v226, v226
	v_exp_f32_e32 v227, v227
	v_exp_f32_e32 v228, v228
	v_exp_f32_e32 v229, v229
	v_pk_mul_f32 v[238:239], v[44:45], v[36:37]
	v_pk_mul_f32 v[240:241], v[46:47], v[38:39]
	v_pk_mul_f32 v[242:243], v[40:41], v[32:33]
	v_pk_mul_f32 v[244:245], v[42:43], v[34:35]
	v_pk_add_f32 v[230:231], v[222:223], v[6:7]
	v_pk_add_f32 v[232:233], v[224:225], v[6:7]
	v_pk_add_f32 v[234:235], v[226:227], v[6:7]
	v_pk_add_f32 v[236:237], v[228:229], v[6:7]
	v_rcp_f32_e32 v230, v230
	v_rcp_f32_e32 v231, v231
	v_rcp_f32_e32 v232, v232
	v_rcp_f32_e32 v233, v233
	v_rcp_f32_e32 v234, v234
	v_rcp_f32_e32 v235, v235
	v_rcp_f32_e32 v236, v236
	v_rcp_f32_e32 v237, v237
	v_pk_mul_f32 v[238:239], v[238:239], v[252:253] op_sel:[0,1] op_sel_hi:[1,1]
	v_pk_mul_f32 v[240:241], v[240:241], v[252:253] op_sel:[0,1] op_sel_hi:[1,1]
	v_pk_mul_f32 v[242:243], v[242:243], v[252:253] op_sel:[0,1] op_sel_hi:[1,1]
	v_pk_mul_f32 v[244:245], v[244:245], v[252:253] op_sel:[0,1] op_sel_hi:[1,1]
	v_pk_mul_f32 v[238:239], v[238:239], v[230:231]
	v_pk_mul_f32 v[240:241], v[240:241], v[232:233]
	v_pk_mul_f32 v[242:243], v[242:243], v[234:235]
	v_pk_mul_f32 v[244:245], v[244:245], v[236:237]
	v_med3_f32 v238, v238, s38, v210
	v_med3_f32 v239, v239, s38, v210
	v_med3_f32 v240, v240, s38, v210
	v_med3_f32 v241, v241, s38, v210
	v_med3_f32 v242, v242, s38, v210
	v_med3_f32 v243, v243, s38, v210
	v_med3_f32 v244, v244, s38, v210
	v_med3_f32 v245, v245, s38, v210
	v_cvt_pk_fp8_f32 v22, v238, v239
	v_cvt_pk_fp8_f32 v23, v242, v243
	v_cvt_pk_fp8_f32 v22, v240, v241 op_sel:[0,0,1]
	v_cvt_pk_fp8_f32 v23, v244, v245 op_sel:[0,0,1]
	s_nop 1
	v_permlane16_swap_b32_e32 v20, v22
	v_permlane16_swap_b32_e32 v21, v23
	s_nop 0
	global_store_dwordx4 v[16:17], v[20:23], off
	s_mov_b64 s[12:13], -1
	s_andn2_b64 vcc, exec, s[10:11]
	s_cbranch_vccnz .LBB0_237
	s_andn2_b64 vcc, exec, s[14:15]
	s_cbranch_vccnz .LBB0_236
	s_barrier
	s_branch .LBB0_236
	s_nop 0
	s_nop 0
	s_nop 0
	s_nop 0
	s_nop 0
	s_nop 0
	s_nop 0
	s_nop 0
	s_nop 0
	s_nop 0
	s_nop 0
	s_nop 0
